# RWKV producers: 112 two-byte stores per wave and round staged through LDS and written as 14 dwordx4 row stores
# speedup vs baseline: 1.0128x; 1.0128x over previous
;     DEVINL bf16_t* VF() const { return (bf16_t*)(ws + OFF_VF); }
; DEVINL bf16_t f2bf(float f) { return (bf16_t)(cvt_pk_bf16(f, 0.f) & 0xffffu); }
; DEVINL float bf2f(bf16_t v) { return __uint_as_float(((unsigned)v) << 16); }
; DEVINL float fexp2(float x) { return __builtin_amdgcn_exp2f(x); }
; DEVINL float flog2(float x) { return __builtin_amdgcn_logf(x); }
; DEVINL float sigmoidf_(float x) { return __builtin_amdgcn_rcpf(1.f + fexp2(-x * LOG2E)); }
; DEVINL void rw_project_head(const Ctx& c, int layer, int b, int hd, int pj, int nP, unsigned* cnt, unsigned char* lds) {
;     ...
; #pragma unroll
;                 for (int rg = 0; rg < 4; ++rg) {
;                     const int tk = kg * 4 + rg;
;                     const bf16_t* rk = RKV + tk * 192 + nt * 16 + cl;
;                     const float rc = bf2f(rk[0]), kc = bf2f(rk[64]), vc = bf2f(rk[128]);
;                     const float u = -(w0c[nt] + aw[rg]);
;                     const float spl = fmaxf(u, 0.f) + flog2(1.f + fexp2(-fabsf(u) * LOG2E)) * (1.f / LOG2E);
;                     ldv[nt][rg] = -fexp2((-spl - 0.5f) * LOG2E) * LOG2E;
;                     const float a = sigmoidf_(a0c[nt] + aa[rg]);
;                     av[nt][rg] = a; gv[nt][rg] = ag[rg]; rcv[nt][rg] = rc;
;                     const float kr = kc * kkc[nt];
;                     kkraw[nt][rg] = kr; ss[rg] += kr * kr;
;                     kmod[nt][rg] = kc * (1.f + (a - 1.f) * kac[nt]);
;                     const size_t o = (size_t)(t0 + tk) * 512 + hd * 64 + nt * 16 + cl;
;                     float vo = vc;
;                     if (layer == 0) c.VF()[o] = f2bf(vc);
;                     else { const float vf = bf2f(c.VF()[o]); vo = vc + (vf - vc) * sigmoidf_(v0c[nt] + avv[rg]); }
;                     vout[nt][rg] = vo;
;                 }
.LBB0_236:
	s_mov_b32 s14, 0xbfb8aa3b
	s_waitcnt vmcnt(7)
	v_add_f32_e32 v38, v157, v38
	s_waitcnt vmcnt(2)
	v_add_f32_e32 v43, v172, v43
	v_lshlrev_b32_e32 v243, 16, v225
	v_max_f32_e64 v225, -v38, 0
	v_mul_f32_e64 v38, |v38|, s14
	v_add_f32_e32 v34, v158, v34
	v_add_f32_e32 v45, v171, v59
	v_mul_f32_e32 v43, 0xbfb8aa3b, v43
	v_exp_f32_e32 v38, v38
	v_mul_f32_e32 v34, 0xbfb8aa3b, v34
	s_waitcnt lgkmcnt(1)
	v_lshlrev_b32_e32 v44, 16, v49
	s_waitcnt lgkmcnt(0)
	v_lshlrev_b32_e32 v49, 16, v52
	v_max_f32_e64 v52, -v45, 0
	v_mul_f32_e64 v45, |v45|, s14
	v_exp_f32_e32 v43, v43
	v_exp_f32_e32 v34, v34
	v_exp_f32_e32 v45, v45
	v_add_f32_e32 v38, 1.0, v38
	v_add_f32_e32 v43, 1.0, v43
	v_log_f32_e32 v38, v38
	v_add_f32_e32 v34, 1.0, v34
	v_add_f32_e32 v45, 1.0, v45
	v_rcp_f32_e32 v43, v43
	v_rcp_f32_e32 v34, v34
	v_log_f32_e32 v45, v45
	v_fmac_f32_e32 v225, 0x3f317218, v38
	v_add_f32_e32 v59, -1.0, v43
	v_sub_f32_e32 v38, -0.5, v225
	v_add_f32_e32 v225, -1.0, v34
	v_fmac_f32_e32 v52, 0x3f317218, v45
	s_waitcnt vmcnt(0)
	v_fma_f32 v59, v174, v59, 1.0
	v_lshlrev_b32_e32 v237, 16, v226
	v_fma_f32 v225, v168, v225, 1.0
	v_add_f32_e32 v31, v153, v31
	v_sub_f32_e32 v45, -0.5, v52
	v_mul_f32_e32 v52, v173, v49
	v_mul_f32_e32 v49, v59, v49
	v_mul_f32_e32 v59, v159, v237
	v_mul_f32_e32 v225, v225, v237
	v_max_f32_e64 v237, -v31, 0
	v_mul_f32_e64 v31, |v31|, s14
	v_add_f32_e32 v27, v154, v27
	v_exp_f32_e32 v31, v31
	v_mul_f32_e32 v27, 0xbfb8aa3b, v27
	v_exp_f32_e32 v27, v27
	v_lshlrev_b32_e32 v233, 16, v223
	v_add_f32_e32 v31, 1.0, v31
	v_log_f32_e32 v31, v31
	v_add_f32_e32 v27, 1.0, v27
	v_rcp_f32_e32 v27, v27
	v_add_f32_e32 v30, v153, v30
	v_fmac_f32_e32 v237, 0x3f317218, v31
	v_sub_f32_e32 v31, -0.5, v237
	v_add_f32_e32 v237, -1.0, v27
	v_fma_f32 v237, v156, v237, 1.0
	v_mul_f32_e32 v54, v155, v233
	v_mul_f32_e32 v233, v237, v233
	v_max_f32_e64 v237, -v30, 0
	v_mul_f32_e64 v30, |v30|, s14
	v_add_f32_e32 v26, v154, v26
	v_exp_f32_e32 v30, v30
	v_mul_f32_e32 v26, 0xbfb8aa3b, v26
	v_exp_f32_e32 v26, v26
	v_lshlrev_b32_e32 v234, 16, v224
	v_add_f32_e32 v30, 1.0, v30
	v_log_f32_e32 v30, v30
	v_add_f32_e32 v26, 1.0, v26
	v_rcp_f32_e32 v26, v26
	v_add_f32_e32 v29, v153, v29
	v_fmac_f32_e32 v237, 0x3f317218, v30
	v_sub_f32_e32 v30, -0.5, v237
	v_add_f32_e32 v237, -1.0, v26
	v_fma_f32 v237, v156, v237, 1.0
	v_mul_f32_e32 v63, v155, v234
	v_mul_f32_e32 v234, v237, v234
	v_max_f32_e64 v237, -v29, 0
	v_mul_f32_e64 v29, |v29|, s14
	v_add_f32_e32 v25, v154, v25
	v_exp_f32_e32 v29, v29
	v_mul_f32_e32 v25, 0xbfb8aa3b, v25
	v_exp_f32_e32 v25, v25
	v_lshlrev_b32_e32 v235, 16, v220
	v_add_f32_e32 v29, 1.0, v29
	v_log_f32_e32 v29, v29
	v_add_f32_e32 v25, 1.0, v25
	v_rcp_f32_e32 v25, v25
	v_add_f32_e32 v28, v153, v28
	v_fmac_f32_e32 v237, 0x3f317218, v29
	v_sub_f32_e32 v29, -0.5, v237
	v_add_f32_e32 v237, -1.0, v25
	v_fma_f32 v237, v156, v237, 1.0
	v_mul_f32_e32 v72, v155, v235
	v_mul_f32_e32 v235, v237, v235
	v_max_f32_e64 v237, -v28, 0
	v_mul_f32_e64 v28, |v28|, s14
	v_add_f32_e32 v24, v154, v24
	v_exp_f32_e32 v28, v28
	v_mul_f32_e32 v24, 0xbfb8aa3b, v24
	v_exp_f32_e32 v24, v24
	v_add_f32_e32 v41, v172, v41
	v_add_f32_e32 v57, v171, v57
	v_mul_f32_e32 v41, 0xbfb8aa3b, v41
	v_add_f32_e32 v28, 1.0, v28
	v_max_f32_e64 v68, -v57, 0
	v_mul_f32_e64 v57, |v57|, s14
	v_exp_f32_e32 v41, v41
	v_log_f32_e32 v28, v28
	v_add_f32_e32 v24, 1.0, v24
	v_exp_f32_e32 v57, v57
	v_rcp_f32_e32 v24, v24
	v_add_f32_e32 v41, 1.0, v41
	v_fmac_f32_e32 v237, 0x3f317218, v28
	v_add_f32_e32 v57, 1.0, v57
	v_rcp_f32_e32 v41, v41
	v_add_f32_e32 v39, v157, v39
	v_sub_f32_e32 v28, -0.5, v237
	v_add_f32_e32 v237, -1.0, v24
	v_lshlrev_b32_e32 v223, 16, v219
	v_log_f32_e32 v57, v57
	v_lshlrev_b32_e32 v236, 16, v217
	v_max_f32_e64 v219, -v39, 0
	v_mul_f32_e64 v39, |v39|, s14
	v_add_f32_e32 v35, v158, v35
	v_fma_f32 v237, v156, v237, 1.0
	v_add_f32_e32 v15, v79, v15
	v_mul_f32_e32 v217, v155, v236
	v_exp_f32_e32 v39, v39
	v_mul_f32_e32 v35, 0xbfb8aa3b, v35
	v_mul_f32_e32 v236, v237, v236
	v_max_f32_e64 v237, -v15, 0
	v_mul_f32_e64 v15, |v15|, s14
	v_exp_f32_e32 v35, v35
	v_exp_f32_e32 v15, v15
	v_add_f32_e32 v150, -1.0, v41
	v_add_f32_e32 v40, v172, v40
	v_lshlrev_b32_e32 v67, 16, v67
	v_fmac_f32_e32 v68, 0x3f317218, v57
	v_fma_f32 v150, v174, v150, 1.0
	v_add_f32_e32 v56, v171, v56
	v_mul_f32_e32 v40, 0xbfb8aa3b, v40
	v_sub_f32_e32 v57, -0.5, v68
	v_mul_f32_e32 v68, v173, v67
	v_mul_f32_e32 v67, v150, v67
	v_max_f32_e64 v150, -v56, 0
	v_mul_f32_e64 v56, |v56|, s14
	v_exp_f32_e32 v40, v40
	v_add_f32_e32 v39, 1.0, v39
	v_add_f32_e32 v11, v87, v11
	v_exp_f32_e32 v56, v56
	v_log_f32_e32 v39, v39
	v_add_f32_e32 v35, 1.0, v35
	v_add_f32_e32 v15, 1.0, v15
	v_mul_f32_e32 v11, 0xbfb8aa3b, v11
	v_rcp_f32_e32 v35, v35
	v_log_f32_e32 v15, v15
	v_exp_f32_e32 v11, v11
	v_add_f32_e32 v40, 1.0, v40
	v_add_f32_e32 v56, 1.0, v56
	v_rcp_f32_e32 v40, v40
	v_fmac_f32_e32 v219, 0x3f317218, v39
	v_log_f32_e32 v56, v56
	v_sub_f32_e32 v39, -0.5, v219
	v_add_f32_e32 v219, -1.0, v35
	v_fmac_f32_e32 v237, 0x3f317218, v15
	v_add_f32_e32 v11, 1.0, v11
	v_lshlrev_b32_e32 v232, 16, v228
	v_fma_f32 v219, v168, v219, 1.0
	v_add_f32_e32 v36, v157, v36
	v_sub_f32_e32 v15, -0.5, v237
	v_rcp_f32_e32 v237, v11
	v_mul_f32_e32 v47, v159, v232
	v_mul_f32_e32 v219, v219, v232
	v_max_f32_e64 v232, -v36, 0
	v_mul_f32_e64 v36, |v36|, s14
	v_add_f32_e32 v32, v158, v32
	v_lshlrev_b32_e32 v242, 16, v227
	v_lshlrev_b32_e32 v227, 16, v215
	v_add_f32_e32 v215, -1.0, v40
	v_exp_f32_e32 v36, v36
	v_mul_f32_e32 v32, 0xbfb8aa3b, v32
	v_lshlrev_b32_e32 v66, 16, v55
	v_add_f32_e32 v55, v171, v58
	v_lshlrev_b32_e32 v73, 16, v73
	v_fmac_f32_e32 v150, 0x3f317218, v56
;     DEVINL bf16_t* VF() const { return (bf16_t*)(ws + OFF_VF); }
; DEVINL bf16_t f2bf(float f) { return (bf16_t)(cvt_pk_bf16(f, 0.f) & 0xffffu); }
; DEVINL float bf2f(bf16_t v) { return __uint_as_float(((unsigned)v) << 16); }
; DEVINL float fexp2(float x) { return __builtin_amdgcn_exp2f(x); }
; DEVINL float flog2(float x) { return __builtin_amdgcn_logf(x); }
; DEVINL float sigmoidf_(float x) { return __builtin_amdgcn_rcpf(1.f + fexp2(-x * LOG2E)); }
; DEVINL float row16_sum(float v) { v += DPPF(v, 0xB1); v += DPPF(v, 0x4E); v += DPPF(v, 0x141); v += DPPF(v, 0x140); return v; }
; DEVINL void rw_project_head(const Ctx& c, int layer, int b, int hd, int pj, int nP, unsigned* cnt, unsigned char* lds) {
;     ...
;                     const float rc = bf2f(rk[0]), kc = bf2f(rk[64]), vc = bf2f(rk[128]);
;                     const float u = -(w0c[nt] + aw[rg]);
;                     const float spl = fmaxf(u, 0.f) + flog2(1.f + fexp2(-fabsf(u) * LOG2E)) * (1.f / LOG2E);
;                     ldv[nt][rg] = -fexp2((-spl - 0.5f) * LOG2E) * LOG2E;
;                     const float a = sigmoidf_(a0c[nt] + aa[rg]);
;                     av[nt][rg] = a; gv[nt][rg] = ag[rg]; rcv[nt][rg] = rc;
;                     const float kr = kc * kkc[nt];
;                     kkraw[nt][rg] = kr; ss[rg] += kr * kr;
;                     kmod[nt][rg] = kc * (1.f + (a - 1.f) * kac[nt]);
;                     const size_t o = (size_t)(t0 + tk) * 512 + hd * 64 + nt * 16 + cl;
;                     float vo = vc;
;                     if (layer == 0) c.VF()[o] = f2bf(vc);
;                     else { const float vf = bf2f(c.VF()[o]); vo = vc + (vf - vc) * sigmoidf_(v0c[nt] + avv[rg]); }
;                     vout[nt][rg] = vo;
;                 }
;             }
;             float inv[4];
; #pragma unroll
;             for (int rg = 0; rg < 4; ++rg) inv[rg] = fminf(__builtin_amdgcn_rsqf(row16_sum(ss[rg])), 1e12f);
	v_fma_f32 v215, v174, v215, 1.0
	v_add_f32_e32 v37, v157, v37
	v_exp_f32_e32 v32, v32
	v_max_f32_e64 v58, -v55, 0
	v_mul_f32_e64 v55, |v55|, s14
	v_add_f32_e32 v42, v172, v42
	v_sub_f32_e32 v56, -0.5, v150
	v_mul_f32_e32 v150, v173, v73
	v_mul_f32_e32 v73, v215, v73
	v_lshlrev_b32_e32 v215, 16, v231
	v_max_f32_e64 v231, -v37, 0
	v_mul_f32_e64 v37, |v37|, s14
	v_add_f32_e32 v33, v158, v33
	v_add_f32_e32 v11, -1.0, v237
	v_lshlrev_b32_e32 v222, 16, v222
	v_exp_f32_e32 v55, v55
	v_mul_f32_e32 v42, 0xbfb8aa3b, v42
	v_exp_f32_e32 v37, v37
	v_mul_f32_e32 v33, 0xbfb8aa3b, v33
	v_fma_f32 v11, v115, v11, 1.0
	v_mul_f32_e32 v61, v113, v222
	v_exp_f32_e32 v42, v42
	v_exp_f32_e32 v33, v33
	v_add_f32_e32 v36, 1.0, v36
	v_mul_f32_e32 v222, v11, v222
	v_add_f32_e32 v11, v79, v14
	v_log_f32_e32 v36, v36
	v_add_f32_e32 v32, 1.0, v32
	v_max_f32_e64 v14, -v11, 0
	v_mul_f32_e64 v11, |v11|, s14
	v_add_f32_e32 v9, v87, v9
	v_rcp_f32_e32 v32, v32
	v_exp_f32_e32 v11, v11
	v_mul_f32_e32 v9, 0xbfb8aa3b, v9
	v_add_f32_e32 v55, 1.0, v55
	v_add_f32_e32 v37, 1.0, v37
	v_exp_f32_e32 v9, v9
	v_log_f32_e32 v55, v55
	v_add_f32_e32 v42, 1.0, v42
	v_log_f32_e32 v37, v37
	v_add_f32_e32 v33, 1.0, v33
	v_add_f32_e32 v10, v87, v10
	v_rcp_f32_e32 v42, v42
	v_rcp_f32_e32 v33, v33
	v_fmac_f32_e32 v232, 0x3f317218, v36
	v_mul_f32_e32 v10, 0xbfb8aa3b, v10
	v_sub_f32_e32 v36, -0.5, v232
	v_add_f32_e32 v232, -1.0, v32
	v_add_f32_e32 v11, 1.0, v11
	v_exp_f32_e32 v10, v10
	v_fma_f32 v232, v168, v232, 1.0
	v_log_f32_e32 v11, v11
	v_add_f32_e32 v9, 1.0, v9
	v_add_f32_e32 v8, v87, v8
	v_fmac_f32_e32 v58, 0x3f317218, v55
	v_mul_f32_e32 v151, v159, v243
	v_fmac_f32_e32 v231, 0x3f317218, v37
	v_mul_f32_e32 v232, v232, v243
	v_rcp_f32_e32 v243, v9
	v_mul_f32_e32 v8, 0xbfb8aa3b, v8
	v_sub_f32_e32 v55, -0.5, v58
	v_add_f32_e32 v58, -1.0, v42
	v_sub_f32_e32 v37, -0.5, v231
	v_add_f32_e32 v231, -1.0, v33
	v_exp_f32_e32 v8, v8
	v_fma_f32 v58, v174, v58, 1.0
	v_fma_f32 v231, v168, v231, 1.0
	v_add_f32_e32 v10, 1.0, v10
	v_mul_f32_e32 v60, v173, v66
	v_mul_f32_e32 v58, v58, v66
	v_mul_f32_e32 v66, v159, v242
	v_mul_f32_e32 v231, v231, v242
	v_fmac_f32_e32 v14, 0x3f317218, v11
	v_rcp_f32_e32 v242, v10
	v_sub_f32_e32 v11, -0.5, v14
	v_add_f32_e32 v9, -1.0, v243
	v_lshlrev_b32_e32 v226, 16, v216
	v_mul_f32_e32 v11, 0x3fb8aa3b, v11
	v_fma_f32 v9, v115, v9, 1.0
	v_add_f32_e32 v8, 1.0, v8
	v_mul_f32_e32 v216, v113, v226
	v_exp_f32_e32 v11, v11
	v_mul_f32_e32 v226, v9, v226
	v_lshlrev_b32_e32 v9, 16, v201
	v_rcp_f32_e32 v201, v8
	v_add_f32_e32 v10, -1.0, v242
	v_mul_f32_e32 v224, v113, v227
	v_mul_f32_e32 v228, v217, v217
	v_fma_f32 v10, v115, v10, 1.0
	v_mul_f32_e32 v71, v113, v223
	v_fmac_f32_e32 v228, v224, v224
	v_mul_f32_e32 v223, v10, v223
	v_add_f32_e32 v10, v79, v13
	v_fmac_f32_e32 v228, v151, v151
	v_mul_f32_e32 v14, 0xbfb8aa3b, v11
	v_max_f32_e64 v11, -v10, 0
	v_mul_f32_e64 v10, |v10|, s14
	v_add_f32_e32 v8, -1.0, v201
	v_fmac_f32_e32 v228, v150, v150
	v_exp_f32_e32 v10, v10
	v_fma_f32 v8, v115, v8, 1.0
	v_mul_f32_e32 v227, v8, v227
	v_mul_f32_e32 v220, v72, v72
	v_add_f32_dpp v8, v228, v228 quad_perm:[1,0,3,2] row_mask:0xf bank_mask:0xf bound_ctrl:1
	v_add_f32_e32 v10, 1.0, v10
	v_log_f32_e32 v10, v10
	v_add_f32_dpp v8, v8, v8 quad_perm:[2,3,0,1] row_mask:0xf bank_mask:0xf bound_ctrl:1
	v_fmac_f32_e32 v220, v216, v216
	v_fmac_f32_e32 v220, v66, v66
	v_add_f32_dpp v8, v8, v8 row_half_mirror row_mask:0xf bank_mask:0xf bound_ctrl:1
	v_fmac_f32_e32 v220, v68, v68
	v_fmac_f32_e32 v11, 0x3f317218, v10
	v_add_f32_dpp v8, v8, v8 row_mirror row_mask:0xf bank_mask:0xf bound_ctrl:1
	v_rsq_f32_e32 v8, v8
	v_sub_f32_e32 v10, -0.5, v11
	v_mul_f32_e32 v10, 0x3fb8aa3b, v10
	v_exp_f32_e32 v10, v10
	v_min_f32_e32 v228, 0x5368d4a5, v8
	v_add_f32_dpp v8, v220, v220 quad_perm:[1,0,3,2] row_mask:0xf bank_mask:0xf bound_ctrl:1
	v_mul_f32_e32 v77, v63, v63
	v_fmac_f32_e32 v77, v71, v71
	v_add_f32_dpp v8, v8, v8 quad_perm:[2,3,0,1] row_mask:0xf bank_mask:0xf bound_ctrl:1
	v_fmac_f32_e32 v77, v59, v59
	v_fmac_f32_e32 v77, v60, v60
	v_add_f32_dpp v8, v8, v8 row_half_mirror row_mask:0xf bank_mask:0xf bound_ctrl:1
	v_mul_f32_e32 v13, 0xbfb8aa3b, v10
	v_add_f32_e32 v10, v79, v12
	v_add_f32_dpp v8, v8, v8 row_mirror row_mask:0xf bank_mask:0xf bound_ctrl:1
	v_rsq_f32_e32 v8, v8
	v_max_f32_e64 v11, -v10, 0
	v_mul_f32_e64 v10, |v10|, s14
	v_exp_f32_e32 v10, v10
	v_min_f32_e32 v220, 0x5368d4a5, v8
	v_add_f32_dpp v8, v77, v77 quad_perm:[1,0,3,2] row_mask:0xf bank_mask:0xf bound_ctrl:1
	v_mul_f32_e32 v69, v54, v54
	v_fmac_f32_e32 v69, v61, v61
	v_add_f32_dpp v8, v8, v8 quad_perm:[2,3,0,1] row_mask:0xf bank_mask:0xf bound_ctrl:1
	v_add_f32_e32 v10, 1.0, v10
	v_fmac_f32_e32 v69, v47, v47
	v_add_f32_dpp v8, v8, v8 row_half_mirror row_mask:0xf bank_mask:0xf bound_ctrl:1
	v_log_f32_e32 v10, v10
	v_fmac_f32_e32 v69, v52, v52
	v_add_f32_dpp v8, v8, v8 row_mirror row_mask:0xf bank_mask:0xf bound_ctrl:1
	v_rsq_f32_e32 v8, v8
	v_fmac_f32_e32 v11, 0x3f317218, v10
	v_sub_f32_e32 v10, -0.5, v11
	v_mul_f32_e32 v10, 0x3fb8aa3b, v10
	v_min_f32_e32 v77, 0x5368d4a5, v8
	v_add_f32_dpp v8, v69, v69 quad_perm:[1,0,3,2] row_mask:0xf bank_mask:0xf bound_ctrl:1
	v_exp_f32_e32 v10, v10
	v_readlane_b32 s22, v245, 28
	v_add_f32_dpp v8, v8, v8 quad_perm:[2,3,0,1] row_mask:0xf bank_mask:0xf bound_ctrl:1
	v_cvt_pk_bf16_f32 v244, v9, s0
	v_readlane_b32 s23, v245, 29
	v_add_f32_dpp v8, v8, v8 row_half_mirror row_mask:0xf bank_mask:0xf bound_ctrl:1
	v_readlane_b32 s14, v247, 30
	v_mul_f32_e32 v12, 0xbfb8aa3b, v10
	v_add_f32_dpp v8, v8, v8 row_mirror row_mask:0xf bank_mask:0xf bound_ctrl:1
	v_rsq_f32_e32 v8, v8
	v_readlane_b32 s15, v247, 31
	v_cvt_pk_bf16_f32 v12, v12, s0
; DEVINL bf16_t f2bf(float f) { return (bf16_t)(cvt_pk_bf16(f, 0.f) & 0xffffu); }
; DEVINL void rw_project_head(const Ctx& c, int layer, int b, int hd, int pj, int nP, unsigned* cnt, unsigned char* lds) {
;     ...
;             for (int nt = 0; nt < 4; ++nt)
; #pragma unroll
;                 for (int rg = 0; rg < 4; ++rg) {
;                     const size_t o = (size_t)(t0 + kg * 4 + rg) * 512 + hd * 64 + nt * 16 + cl;
;                     const float kk = kkraw[nt][rg] * inv[rg];
;                     R[o] = f2bf(rcv[nt][rg]); LD[o] = f2bf(ldv[nt][rg]); KP[o] = f2bf(kmod[nt][rg]); VP[o] = f2bf(vout[nt][rg]);
;                     KK[o] = f2bf(kk); BB[o] = f2bf(kk * av[nt][rg]); GG[o] = f2bf(gv[nt][rg]);
;                 }
	v_readlane_b32 s24, v247, 32
	v_min_f32_e32 v69, 0x5368d4a5, v8
	v_lshrrev_b32_e32 v251, 6, v160
	v_mul_u32_u24_e32 v251, 0x3d00, v251
	v_add_u32_e32 v251, 0x9400, v251
	v_lshlrev_b64 v[8:9], 1, v[128:129]
	v_lshrrev_b32_e32 v248, 3, v8
	v_and_b32_e32 v248, 0x780, v248
	v_and_b32_e32 v250, 0x7e, v8
	v_add3_u32 v248, v248, v250, v251
	v_mov_b32_e32 v10, v248
	ds_write_b16 v10, v244
	v_add_u32_e32 v10, 0x800, v248
	ds_write_b16 v10, v12
	v_cvt_pk_bf16_f32 v12, v227, s0
	v_add_u32_e32 v10, 0x1000, v248
	v_readlane_b32 s25, v247, 33
	v_readlane_b32 s28, v247, 34
	v_mul_f32_e32 v224, v224, v228
	ds_write_b16 v10, v12
	v_cvt_pk_bf16_f32 v12, v64, s0
	v_add_u32_e32 v10, 0x1800, v248
	v_readlane_b32 s29, v247, 35
	ds_write_b16 v10, v12
	v_cvt_pk_bf16_f32 v12, v224, s0
	v_add_u32_e32 v10, 0x2000, v248
	v_readlane_b32 s30, v247, 36
	v_readlane_b32 s34, v247, 38
	ds_write_b16 v10, v12
	v_mul_f32_e32 v10, v201, v224
	v_readlane_b32 s31, v247, 37
	v_readlane_b32 s35, v247, 39
	v_cvt_pk_bf16_f32 v12, v10, s0
	v_add_u32_e32 v10, 0x2800, v248
	v_cvt_pk_bf16_f32 v0, v0, s0
	v_add_u32_e32 v8, 0x3000, v248
	v_lshlrev_b32_e32 v206, 16, v206
	ds_write_b16 v8, v0
	v_lshlrev_b64 v[8:9], 1, v[130:131]
	v_lshrrev_b32_e32 v248, 3, v8
	v_and_b32_e32 v248, 0x780, v248
	v_and_b32_e32 v250, 0x7e, v8
	v_add3_u32 v248, v248, v250, v251
	ds_write_b16 v10, v12
	v_cvt_pk_bf16_f32 v12, v206, s0
	v_mov_b32_e32 v10, v248
	ds_write_b16 v10, v12
	v_cvt_pk_bf16_f32 v12, v13, s0
	v_add_u32_e32 v10, 0x800, v248
	ds_write_b16 v10, v12
	v_cvt_pk_bf16_f32 v12, v226, s0
	v_add_u32_e32 v10, 0x1000, v248
	v_mul_f32_e32 v0, v216, v220
	ds_write_b16 v10, v12
	v_cvt_pk_bf16_f32 v12, v119, s0
	v_add_u32_e32 v10, 0x1800, v248
	ds_write_b16 v10, v12
	v_cvt_pk_bf16_f32 v12, v0, s0
	v_add_u32_e32 v10, 0x2000, v248
	v_mul_f32_e32 v0, v243, v0
	ds_write_b16 v10, v12
	v_cvt_pk_bf16_f32 v0, v0, s0
	v_add_u32_e32 v10, 0x2800, v248
	ds_write_b16 v10, v0
	v_cvt_pk_bf16_f32 v10, v1, s0
	v_add_u32_e32 v0, 0x3000, v248
	v_lshlrev_b32_e32 v210, 16, v210
	ds_write_b16 v0, v10
	v_lshlrev_b64 v[0:1], 1, v[132:133]
	v_lshrrev_b32_e32 v249, 3, v0
	v_and_b32_e32 v249, 0x780, v249
	v_and_b32_e32 v250, 0x7e, v0
	v_add3_u32 v249, v249, v250, v251
	v_cvt_pk_bf16_f32 v11, v210, s0
	v_mov_b32_e32 v8, v249
	ds_write_b16 v8, v11
	v_cvt_pk_bf16_f32 v11, v14, s0
	v_add_u32_e32 v8, 0x800, v249
	ds_write_b16 v8, v11
	v_cvt_pk_bf16_f32 v11, v223, s0
	v_add_u32_e32 v8, 0x1000, v249
	v_mul_f32_e32 v15, 0x3fb8aa3b, v15
	v_mul_f32_e32 v10, v71, v77
	ds_write_b16 v8, v11
	v_cvt_pk_bf16_f32 v11, v199, s0
	v_add_u32_e32 v8, 0x1800, v249
	v_exp_f32_e32 v15, v15
	ds_write_b16 v8, v11
	v_cvt_pk_bf16_f32 v11, v10, s0
	v_add_u32_e32 v8, 0x2000, v249
	ds_write_b16 v8, v11
	v_mul_f32_e32 v8, v242, v10
	v_cvt_pk_bf16_f32 v10, v8, s0
	v_add_u32_e32 v8, 0x2800, v249
	v_cvt_pk_bf16_f32 v2, v2, s0
	v_add_u32_e32 v0, 0x3000, v249
	v_lshlrev_b32_e32 v211, 16, v211
	ds_write_b16 v0, v2
	v_lshlrev_b64 v[0:1], 1, v[134:135]
	v_lshrrev_b32_e32 v249, 3, v0
	v_and_b32_e32 v249, 0x780, v249
	v_and_b32_e32 v250, 0x7e, v0
	v_add3_u32 v249, v249, v250, v251
	v_mul_f32_e32 v15, 0xbfb8aa3b, v15
	ds_write_b16 v8, v10
	v_cvt_pk_bf16_f32 v10, v211, s0
	v_mov_b32_e32 v8, v249
	ds_write_b16 v8, v10
	v_cvt_pk_bf16_f32 v10, v15, s0
	v_add_u32_e32 v8, 0x800, v249
	ds_write_b16 v8, v10
	v_cvt_pk_bf16_f32 v10, v222, s0
	v_add_u32_e32 v8, 0x1000, v249
	v_mul_f32_e32 v28, 0x3fb8aa3b, v28
	v_mul_f32_e32 v2, v61, v69
	ds_write_b16 v8, v10
	v_cvt_pk_bf16_f32 v10, v200, s0
	v_add_u32_e32 v8, 0x1800, v249
	v_exp_f32_e32 v28, v28
	ds_write_b16 v8, v10
	v_cvt_pk_bf16_f32 v10, v2, s0
	v_add_u32_e32 v8, 0x2000, v249
	v_mul_f32_e32 v2, v237, v2
	ds_write_b16 v8, v10
	v_cvt_pk_bf16_f32 v2, v2, s0
	v_add_u32_e32 v8, 0x2800, v249
	ds_write_b16 v8, v2
	v_cvt_pk_bf16_f32 v2, v3, s0
	v_add_u32_e32 v0, 0x3000, v249
	v_lshlrev_b32_e32 v212, 16, v212
	ds_write_b16 v0, v2
	v_lshlrev_b64 v[0:1], 1, v[136:137]
	v_lshrrev_b32_e32 v249, 3, v0
	v_and_b32_e32 v249, 0x780, v249
	v_and_b32_e32 v250, 0x7e, v0
	v_add3_u32 v249, v249, v250, v251
	v_mul_f32_e32 v28, 0xbfb8aa3b, v28
	v_cvt_pk_bf16_f32 v9, v212, s0
	v_mov_b32_e32 v2, v249
	ds_write_b16 v2, v9
	v_cvt_pk_bf16_f32 v9, v28, s0
	v_add_u32_e32 v2, 0x800, v249
	ds_write_b16 v2, v9
	v_cvt_pk_bf16_f32 v9, v236, s0
	v_add_u32_e32 v2, 0x1000, v249
	v_mul_f32_e32 v8, v217, v228
	ds_write_b16 v2, v9
	v_cvt_pk_bf16_f32 v9, v202, s0
	v_add_u32_e32 v2, 0x1800, v249
	v_mul_f32_e32 v29, 0x3fb8aa3b, v29
	ds_write_b16 v2, v9
	v_cvt_pk_bf16_f32 v9, v8, s0
	v_add_u32_e32 v2, 0x2000, v249
	v_exp_f32_e32 v29, v29
	ds_write_b16 v2, v9
	v_mul_f32_e32 v2, v24, v8
	v_cvt_pk_bf16_f32 v8, v2, s0
	v_add_u32_e32 v2, 0x2800, v249
	ds_write_b16 v2, v8
	v_cvt_pk_bf16_f32 v2, v4, s0
	v_add_u32_e32 v0, 0x3000, v249
	v_lshlrev_b32_e32 v213, 16, v213
	ds_write_b16 v0, v2
	v_lshlrev_b64 v[0:1], 1, v[138:139]
	v_lshrrev_b32_e32 v249, 3, v0
	v_and_b32_e32 v249, 0x780, v249
	v_and_b32_e32 v250, 0x7e, v0
	v_add3_u32 v249, v249, v250, v251
	v_mul_f32_e32 v29, 0xbfb8aa3b, v29
	v_cvt_pk_bf16_f32 v8, v213, s0
	v_mov_b32_e32 v2, v249
	ds_write_b16 v2, v8
	v_cvt_pk_bf16_f32 v8, v29, s0
	v_add_u32_e32 v2, 0x800, v249
	ds_write_b16 v2, v8
	v_cvt_pk_bf16_f32 v8, v235, s0
	v_add_u32_e32 v2, 0x1000, v249
	v_mul_f32_e32 v4, v72, v220
	ds_write_b16 v2, v8
	v_cvt_pk_bf16_f32 v8, v203, s0
	v_add_u32_e32 v2, 0x1800, v249
	v_mul_f32_e32 v30, 0x3fb8aa3b, v30
	ds_write_b16 v2, v8
	v_cvt_pk_bf16_f32 v8, v4, s0
	v_add_u32_e32 v2, 0x2000, v249
	v_exp_f32_e32 v30, v30
	ds_write_b16 v2, v8
	v_mul_f32_e32 v2, v25, v4
	v_cvt_pk_bf16_f32 v4, v2, s0
	v_add_u32_e32 v2, 0x2800, v249
	ds_write_b16 v2, v4
; DEVINL bf16_t f2bf(float f) { return (bf16_t)(cvt_pk_bf16(f, 0.f) & 0xffffu); }
; DEVINL void rw_project_head(const Ctx& c, int layer, int b, int hd, int pj, int nP, unsigned* cnt, unsigned char* lds) {
;     ...
;             for (int nt = 0; nt < 4; ++nt)
; #pragma unroll
;                 for (int rg = 0; rg < 4; ++rg) {
;                     const size_t o = (size_t)(t0 + kg * 4 + rg) * 512 + hd * 64 + nt * 16 + cl;
;                     const float kk = kkraw[nt][rg] * inv[rg];
;                     R[o] = f2bf(rcv[nt][rg]); LD[o] = f2bf(ldv[nt][rg]); KP[o] = f2bf(kmod[nt][rg]); VP[o] = f2bf(vout[nt][rg]);
;                     KK[o] = f2bf(kk); BB[o] = f2bf(kk * av[nt][rg]); GG[o] = f2bf(gv[nt][rg]);
;                 }
	v_cvt_pk_bf16_f32 v2, v5, s0
	v_add_u32_e32 v0, 0x3000, v249
	v_lshlrev_b32_e32 v214, 16, v214
	ds_write_b16 v0, v2
	v_lshlrev_b64 v[0:1], 1, v[140:141]
	v_lshrrev_b32_e32 v249, 3, v0
	v_and_b32_e32 v249, 0x780, v249
	v_and_b32_e32 v250, 0x7e, v0
	v_add3_u32 v249, v249, v250, v251
	v_mul_f32_e32 v30, 0xbfb8aa3b, v30
	v_cvt_pk_bf16_f32 v5, v214, s0
	v_mov_b32_e32 v2, v249
	ds_write_b16 v2, v5
	v_cvt_pk_bf16_f32 v5, v30, s0
	v_add_u32_e32 v2, 0x800, v249
	ds_write_b16 v2, v5
	v_cvt_pk_bf16_f32 v5, v234, s0
	v_add_u32_e32 v2, 0x1000, v249
	v_mul_f32_e32 v4, v63, v77
	ds_write_b16 v2, v5
	v_cvt_pk_bf16_f32 v5, v204, s0
	v_add_u32_e32 v2, 0x1800, v249
	v_mul_f32_e32 v31, 0x3fb8aa3b, v31
	ds_write_b16 v2, v5
	v_cvt_pk_bf16_f32 v5, v4, s0
	v_add_u32_e32 v2, 0x2000, v249
	v_exp_f32_e32 v31, v31
	ds_write_b16 v2, v5
	v_mul_f32_e32 v2, v26, v4
	v_cvt_pk_bf16_f32 v4, v2, s0
	v_add_u32_e32 v2, 0x2800, v249
	ds_write_b16 v2, v4
	v_cvt_pk_bf16_f32 v2, v6, s0
	v_add_u32_e32 v0, 0x3000, v249
	v_lshlrev_b32_e32 v218, 16, v218
	ds_write_b16 v0, v2
	v_lshlrev_b64 v[0:1], 1, v[142:143]
	v_lshrrev_b32_e32 v249, 3, v0
	v_and_b32_e32 v249, 0x780, v249
	v_and_b32_e32 v250, 0x7e, v0
	v_add3_u32 v249, v249, v250, v251
	v_mul_f32_e32 v31, 0xbfb8aa3b, v31
	v_cvt_pk_bf16_f32 v5, v218, s0
	v_mov_b32_e32 v2, v249
	ds_write_b16 v2, v5
	v_cvt_pk_bf16_f32 v5, v31, s0
	v_add_u32_e32 v2, 0x800, v249
	ds_write_b16 v2, v5
	v_cvt_pk_bf16_f32 v5, v233, s0
	v_add_u32_e32 v2, 0x1000, v249
	v_mul_f32_e32 v4, v54, v69
	ds_write_b16 v2, v5
	v_cvt_pk_bf16_f32 v5, v205, s0
	v_add_u32_e32 v2, 0x1800, v249
	v_mul_f32_e32 v36, 0x3fb8aa3b, v36
	ds_write_b16 v2, v5
	v_cvt_pk_bf16_f32 v5, v4, s0
	v_add_u32_e32 v2, 0x2000, v249
	v_exp_f32_e32 v36, v36
	ds_write_b16 v2, v5
	v_mul_f32_e32 v2, v27, v4
	v_cvt_pk_bf16_f32 v4, v2, s0
	v_add_u32_e32 v2, 0x2800, v249
	ds_write_b16 v2, v4
	v_cvt_pk_bf16_f32 v2, v7, s0
	v_add_u32_e32 v0, 0x3000, v249
	v_lshlrev_b32_e32 v230, 16, v230
	ds_write_b16 v0, v2
	v_lshlrev_b64 v[0:1], 1, v[144:145]
	v_lshrrev_b32_e32 v249, 3, v0
	v_and_b32_e32 v249, 0x780, v249
	v_and_b32_e32 v250, 0x7e, v0
	v_add3_u32 v249, v249, v250, v251
	v_mul_f32_e32 v36, 0xbfb8aa3b, v36
	v_cvt_pk_bf16_f32 v5, v230, s0
	v_mov_b32_e32 v2, v249
	ds_write_b16 v2, v5
	v_cvt_pk_bf16_f32 v5, v36, s0
	v_add_u32_e32 v2, 0x800, v249
	ds_write_b16 v2, v5
	v_cvt_pk_bf16_f32 v5, v232, s0
	v_add_u32_e32 v2, 0x1000, v249
	v_mul_f32_e32 v4, v151, v228
	ds_write_b16 v2, v5
	v_cvt_pk_bf16_f32 v5, v207, s0
	v_add_u32_e32 v2, 0x1800, v249
	v_mul_f32_e32 v37, 0x3fb8aa3b, v37
	ds_write_b16 v2, v5
	v_cvt_pk_bf16_f32 v5, v4, s0
	v_add_u32_e32 v2, 0x2000, v249
	v_exp_f32_e32 v37, v37
	ds_write_b16 v2, v5
	v_mul_f32_e32 v2, v32, v4
	v_cvt_pk_bf16_f32 v4, v2, s0
	v_add_u32_e32 v2, 0x2800, v249
	ds_write_b16 v2, v4
	v_cvt_pk_bf16_f32 v2, v16, s0
	v_add_u32_e32 v0, 0x3000, v249
	v_lshlrev_b32_e32 v229, 16, v229
	ds_write_b16 v0, v2
	v_lshlrev_b64 v[0:1], 1, v[146:147]
	v_lshrrev_b32_e32 v249, 3, v0
	v_and_b32_e32 v249, 0x780, v249
	v_and_b32_e32 v250, 0x7e, v0
	v_add3_u32 v249, v249, v250, v251
	v_mul_f32_e32 v37, 0xbfb8aa3b, v37
	v_cvt_pk_bf16_f32 v5, v229, s0
	v_mov_b32_e32 v2, v249
	ds_write_b16 v2, v5
	v_cvt_pk_bf16_f32 v5, v37, s0
	v_add_u32_e32 v2, 0x800, v249
	ds_write_b16 v2, v5
	v_cvt_pk_bf16_f32 v5, v231, s0
	v_add_u32_e32 v2, 0x1000, v249
	v_mul_f32_e32 v4, v66, v220
	ds_write_b16 v2, v5
	v_cvt_pk_bf16_f32 v5, v208, s0
	v_add_u32_e32 v2, 0x1800, v249
	v_mul_f32_e32 v38, 0x3fb8aa3b, v38
	ds_write_b16 v2, v5
	v_cvt_pk_bf16_f32 v5, v4, s0
	v_add_u32_e32 v2, 0x2000, v249
	v_exp_f32_e32 v38, v38
	ds_write_b16 v2, v5
	v_mul_f32_e32 v2, v33, v4
	v_cvt_pk_bf16_f32 v4, v2, s0
	v_add_u32_e32 v2, 0x2800, v249
	ds_write_b16 v2, v4
	v_cvt_pk_bf16_f32 v2, v17, s0
	v_add_u32_e32 v0, 0x3000, v249
	v_lshlrev_b32_e32 v221, 16, v221
	ds_write_b16 v0, v2
	v_lshlrev_b64 v[0:1], 1, v[74:75]
	v_lshrrev_b32_e32 v249, 3, v0
	v_and_b32_e32 v249, 0x780, v249
	v_and_b32_e32 v250, 0x7e, v0
	v_add3_u32 v249, v249, v250, v251
	v_mul_f32_e32 v38, 0xbfb8aa3b, v38
	v_cvt_pk_bf16_f32 v5, v221, s0
	v_mov_b32_e32 v2, v249
	ds_write_b16 v2, v5
	v_cvt_pk_bf16_f32 v5, v38, s0
	v_add_u32_e32 v2, 0x800, v249
	ds_write_b16 v2, v5
	v_cvt_pk_bf16_f32 v5, v225, s0
	v_add_u32_e32 v2, 0x1000, v249
	v_mul_f32_e32 v4, v59, v77
	ds_write_b16 v2, v5
	v_cvt_pk_bf16_f32 v5, v209, s0
	v_add_u32_e32 v2, 0x1800, v249
	v_mul_f32_e32 v39, 0x3fb8aa3b, v39
	ds_write_b16 v2, v5
	v_cvt_pk_bf16_f32 v5, v4, s0
	v_add_u32_e32 v2, 0x2000, v249
	v_exp_f32_e32 v39, v39
	ds_write_b16 v2, v5
	v_mul_f32_e32 v2, v34, v4
	v_cvt_pk_bf16_f32 v4, v2, s0
	v_add_u32_e32 v2, 0x2800, v249
	ds_write_b16 v2, v4
	v_cvt_pk_bf16_f32 v2, v18, s0
	v_add_u32_e32 v0, 0x3000, v249
	ds_write_b16 v0, v2
	v_lshlrev_b64 v[0:1], 1, v[148:149]
	v_lshrrev_b32_e32 v249, 3, v0
	v_and_b32_e32 v249, 0x780, v249
	v_and_b32_e32 v250, 0x7e, v0
	v_add3_u32 v249, v249, v250, v251
	v_mul_f32_e32 v39, 0xbfb8aa3b, v39
	v_cvt_pk_bf16_f32 v5, v215, s0
	v_mov_b32_e32 v2, v249
	ds_write_b16 v2, v5
	v_cvt_pk_bf16_f32 v5, v39, s0
	v_add_u32_e32 v2, 0x800, v249
	ds_write_b16 v2, v5
	v_cvt_pk_bf16_f32 v5, v219, s0
	v_add_u32_e32 v2, 0x1000, v249
	v_mul_f32_e32 v4, v47, v69
	ds_write_b16 v2, v5
	v_cvt_pk_bf16_f32 v5, v76, s0
	v_add_u32_e32 v2, 0x1800, v249
	v_mul_f32_e32 v56, 0x3fb8aa3b, v56
	ds_write_b16 v2, v5
	v_cvt_pk_bf16_f32 v5, v4, s0
	v_add_u32_e32 v2, 0x2000, v249
	v_exp_f32_e32 v56, v56
	ds_write_b16 v2, v5
	v_mul_f32_e32 v2, v35, v4
	v_cvt_pk_bf16_f32 v4, v2, s0
	v_add_u32_e32 v2, 0x2800, v249
	ds_write_b16 v2, v4
	v_cvt_pk_bf16_f32 v2, v19, s0
	v_add_u32_e32 v0, 0x3000, v249
	v_lshlrev_b32_e32 v70, 16, v70
; DEVINL bf16_t f2bf(float f) { return (bf16_t)(cvt_pk_bf16(f, 0.f) & 0xffffu); }
; DEVINL void rw_project_head(const Ctx& c, int layer, int b, int hd, int pj, int nP, unsigned* cnt, unsigned char* lds) {
;     ...
;             for (int nt = 0; nt < 4; ++nt)
; #pragma unroll
;                 for (int rg = 0; rg < 4; ++rg) {
;                     const size_t o = (size_t)(t0 + kg * 4 + rg) * 512 + hd * 64 + nt * 16 + cl;
;                     const float kk = kkraw[nt][rg] * inv[rg];
;                     R[o] = f2bf(rcv[nt][rg]); LD[o] = f2bf(ldv[nt][rg]); KP[o] = f2bf(kmod[nt][rg]); VP[o] = f2bf(vout[nt][rg]);
;                     KK[o] = f2bf(kk); BB[o] = f2bf(kk * av[nt][rg]); GG[o] = f2bf(gv[nt][rg]);
;                 }
	ds_write_b16 v0, v2
	v_lshlrev_b64 v[0:1], 1, v[120:121]
	v_lshrrev_b32_e32 v249, 3, v0
	v_and_b32_e32 v249, 0x780, v249
	v_and_b32_e32 v250, 0x7e, v0
	v_add3_u32 v249, v249, v250, v251
	v_mul_f32_e32 v56, 0xbfb8aa3b, v56
	v_cvt_pk_bf16_f32 v5, v70, s0
	v_mov_b32_e32 v2, v249
	ds_write_b16 v2, v5
	v_cvt_pk_bf16_f32 v5, v56, s0
	v_add_u32_e32 v2, 0x800, v249
	ds_write_b16 v2, v5
	v_cvt_pk_bf16_f32 v5, v73, s0
	v_add_u32_e32 v2, 0x1000, v249
	v_mul_f32_e32 v4, v150, v228
	ds_write_b16 v2, v5
	v_cvt_pk_bf16_f32 v5, v50, s0
	v_add_u32_e32 v2, 0x1800, v249
	v_mul_f32_e32 v57, 0x3fb8aa3b, v57
	ds_write_b16 v2, v5
	v_cvt_pk_bf16_f32 v5, v4, s0
	v_add_u32_e32 v2, 0x2000, v249
	v_exp_f32_e32 v57, v57
	ds_write_b16 v2, v5
	v_mul_f32_e32 v2, v40, v4
	v_cvt_pk_bf16_f32 v4, v2, s0
	v_add_u32_e32 v2, 0x2800, v249
	ds_write_b16 v2, v4
	v_cvt_pk_bf16_f32 v2, v20, s0
	v_add_u32_e32 v0, 0x3000, v249
	v_lshlrev_b32_e32 v62, 16, v62
	ds_write_b16 v0, v2
	v_lshlrev_b64 v[0:1], 1, v[122:123]
	v_lshrrev_b32_e32 v249, 3, v0
	v_and_b32_e32 v249, 0x780, v249
	v_and_b32_e32 v250, 0x7e, v0
	v_add3_u32 v249, v249, v250, v251
	v_mul_f32_e32 v57, 0xbfb8aa3b, v57
	v_cvt_pk_bf16_f32 v5, v62, s0
	v_mov_b32_e32 v2, v249
	ds_write_b16 v2, v5
	v_cvt_pk_bf16_f32 v5, v57, s0
	v_add_u32_e32 v2, 0x800, v249
	ds_write_b16 v2, v5
	v_cvt_pk_bf16_f32 v5, v67, s0
	v_add_u32_e32 v2, 0x1000, v249
	v_mul_f32_e32 v4, v68, v220
	ds_write_b16 v2, v5
	v_cvt_pk_bf16_f32 v5, v51, s0
	v_add_u32_e32 v2, 0x1800, v249
	v_mul_f32_e32 v55, 0x3fb8aa3b, v55
	ds_write_b16 v2, v5
	v_cvt_pk_bf16_f32 v5, v4, s0
	v_add_u32_e32 v2, 0x2000, v249
	v_exp_f32_e32 v55, v55
	ds_write_b16 v2, v5
	v_mul_f32_e32 v2, v41, v4
	v_cvt_pk_bf16_f32 v4, v2, s0
	v_add_u32_e32 v2, 0x2800, v249
	ds_write_b16 v2, v4
	v_cvt_pk_bf16_f32 v2, v21, s0
	v_add_u32_e32 v0, 0x3000, v249
	v_lshlrev_b32_e32 v53, 16, v53
	ds_write_b16 v0, v2
	v_lshlrev_b64 v[0:1], 1, v[124:125]
	v_lshrrev_b32_e32 v249, 3, v0
	v_and_b32_e32 v249, 0x780, v249
	v_and_b32_e32 v250, 0x7e, v0
	v_add3_u32 v249, v249, v250, v251
	v_mul_f32_e32 v55, 0xbfb8aa3b, v55
	v_cvt_pk_bf16_f32 v5, v53, s0
	v_mov_b32_e32 v2, v249
	ds_write_b16 v2, v5
	v_cvt_pk_bf16_f32 v5, v55, s0
	v_add_u32_e32 v2, 0x800, v249
	ds_write_b16 v2, v5
	v_cvt_pk_bf16_f32 v5, v58, s0
	v_add_u32_e32 v2, 0x1000, v249
	v_mul_f32_e32 v4, v60, v77
	ds_write_b16 v2, v5
	v_cvt_pk_bf16_f32 v5, v48, s0
	v_add_u32_e32 v2, 0x1800, v249
	v_mul_f32_e32 v45, 0x3fb8aa3b, v45
	ds_write_b16 v2, v5
	v_cvt_pk_bf16_f32 v5, v4, s0
	v_add_u32_e32 v2, 0x2000, v249
	v_exp_f32_e32 v45, v45
	ds_write_b16 v2, v5
	v_mul_f32_e32 v2, v42, v4
	v_cvt_pk_bf16_f32 v4, v2, s0
	v_add_u32_e32 v2, 0x2800, v249
	ds_write_b16 v2, v4
	v_cvt_pk_bf16_f32 v2, v22, s0
	v_add_u32_e32 v0, 0x3000, v249
	ds_write_b16 v0, v2
	v_lshlrev_b64 v[0:1], 1, v[126:127]
	v_lshrrev_b32_e32 v249, 3, v0
	v_and_b32_e32 v249, 0x780, v249
	v_and_b32_e32 v250, 0x7e, v0
	v_add3_u32 v249, v249, v250, v251
	v_mul_f32_e32 v45, 0xbfb8aa3b, v45
	v_cvt_pk_bf16_f32 v5, v44, s0
	v_mov_b32_e32 v2, v249
	ds_write_b16 v2, v5
	v_cvt_pk_bf16_f32 v5, v45, s0
	v_add_u32_e32 v2, 0x800, v249
	ds_write_b16 v2, v5
	v_cvt_pk_bf16_f32 v5, v49, s0
	v_add_u32_e32 v2, 0x1000, v249
	v_mul_f32_e32 v4, v52, v69
	ds_write_b16 v2, v5
	v_add_u32_e32 v2, 0x1800, v249
	ds_write_b16 v2, v46
	v_cvt_pk_bf16_f32 v5, v4, s0
	v_add_u32_e32 v2, 0x2000, v249
	ds_write_b16 v2, v5
	v_mul_f32_e32 v2, v43, v4
	v_cvt_pk_bf16_f32 v4, v2, s0
	v_add_u32_e32 v2, 0x2800, v249
	ds_write_b16 v2, v4
	v_cvt_pk_bf16_f32 v2, v23, s0
	v_add_u32_e32 v0, 0x3000, v249
	ds_write_b16 v0, v2
	v_and_b32_e32 v252, 63, v160
	v_lshl_add_u32 v252, v252, 4, v251
	v_and_b32_e32 v253, 0xfffffff0, v195
	v_add_u32_e32 v253, v253, v186
	v_bfe_u32 v254, v160, 3, 3
	v_add_u32_e32 v253, v253, v254
	v_lshlrev_b32_e32 v253, 9, v253
	v_and_b32_e32 v254, 0x1c0, v86
	v_add_u32_e32 v253, v253, v254
	v_and_b32_e32 v254, 7, v160
	v_lshl_add_u32 v253, v254, 3, v253
	v_lshlrev_b32_e32 v254, 1, v253
	v_mov_b32_e32 v255, 0
	v_add_u32_e32 v248, 0x2000, v254
	v_mov_b32_e32 v249, 0
	ds_read_b128 v[8:11], v252 offset:0
	ds_read_b128 v[28:31], v252 offset:1024
	ds_read_b128 v[36:39], v252 offset:2048
	ds_read_b128 v[0:3], v252 offset:3072
	s_waitcnt lgkmcnt(0)
	v_lshl_add_u64 v[4:5], s[22:23], 0, v[254:255]
	global_store_dwordx4 v[4:5], v[8:11], off
	v_lshl_add_u64 v[250:251], s[22:23], 0, v[248:249]
	global_store_dwordx4 v[250:251], v[28:31], off
	v_lshl_add_u64 v[4:5], s[14:15], 0, v[254:255]
	global_store_dwordx4 v[4:5], v[36:39], off
	v_lshl_add_u64 v[250:251], s[14:15], 0, v[248:249]
	global_store_dwordx4 v[250:251], v[0:3], off
	ds_read_b128 v[8:11], v252 offset:4096
	ds_read_b128 v[28:31], v252 offset:5120
	ds_read_b128 v[36:39], v252 offset:6144
	ds_read_b128 v[0:3], v252 offset:7168
	s_waitcnt lgkmcnt(0)
	v_lshl_add_u64 v[4:5], s[0:1], 0, v[254:255]
	global_store_dwordx4 v[4:5], v[8:11], off
	v_lshl_add_u64 v[250:251], s[0:1], 0, v[248:249]
	global_store_dwordx4 v[250:251], v[28:31], off
	v_lshl_add_u64 v[4:5], s[24:25], 0, v[254:255]
	global_store_dwordx4 v[4:5], v[36:39], off
	v_lshl_add_u64 v[250:251], s[24:25], 0, v[248:249]
	global_store_dwordx4 v[250:251], v[0:3], off
	ds_read_b128 v[8:11], v252 offset:8192
	ds_read_b128 v[28:31], v252 offset:9216
	ds_read_b128 v[36:39], v252 offset:10240
	ds_read_b128 v[0:3], v252 offset:11264
	s_waitcnt lgkmcnt(0)
	v_lshl_add_u64 v[4:5], s[28:29], 0, v[254:255]
	global_store_dwordx4 v[4:5], v[8:11], off
	v_lshl_add_u64 v[250:251], s[28:29], 0, v[248:249]
	global_store_dwordx4 v[250:251], v[28:31], off
	v_lshl_add_u64 v[4:5], s[30:31], 0, v[254:255]
	global_store_dwordx4 v[4:5], v[36:39], off
	v_lshl_add_u64 v[250:251], s[30:31], 0, v[248:249]
	global_store_dwordx4 v[250:251], v[0:3], off
	ds_read_b128 v[8:11], v252 offset:12288
	ds_read_b128 v[28:31], v252 offset:13312
	s_waitcnt lgkmcnt(0)
	v_lshl_add_u64 v[4:5], s[34:35], 0, v[254:255]
	global_store_dwordx4 v[4:5], v[8:11], off
	v_lshl_add_u64 v[250:251], s[34:35], 0, v[248:249]
	global_store_dwordx4 v[250:251], v[28:31], off
